# v84 + no grid barrier between the context-row phase and the QKV GEMM (completion counter; only the 16 workgroups owning a context QKV unit wait, before that unit's tiles are prefetched)
# speedup vs baseline: 1.0029x; 1.0029x over previous
; __device__ __forceinline__ unsigned pk2(float lo, float hi) { return pg8::cvt_pk_bf16(lo, hi); }
; __device__ __forceinline__ float bf_lo(unsigned w) { return __uint_as_float(w << 16); }
; __device__ __forceinline__ float bf_hi(unsigned w) { return __uint_as_float(w & 0xffff0000u); }
; #define CACC  WSP(float, WS_G)
; #define SSQ    WSP(float, WS_SSQ)
; __global__ void __launch_bounds__(NWAVES * 64, 2) fwd_kernel(Args args) {
;     ...
;                 for (int r = gw; r < MCTX; r += NGW) { const f32x4* xr = (const f32x4*)(CACC + (size_t)r * DM) + lane; unsigned long long* h8 = (unsigned long long*)(H16 + (size_t)(MLAT + r) * DM) + lane; f32x4 v[4]; float ss = 0.f;
; #pragma unroll
;                     for (int j = 0; j < 4; ++j) { const unsigned long long hw_ = h8[64 * j]; const unsigned lo_ = (unsigned)hw_, hi_ = (unsigned)(hw_ >> 32);
;                         v[j] = (f32x4){bf_lo(lo_), bf_hi(lo_), bf_lo(hi_), bf_hi(hi_)} + ((xr[64 * j] + xr[64 * j + MCTX * DM / 4]) + (xr[64 * j + 2 * (MCTX * DM / 4)] + xr[64 * j + 3 * (MCTX * DM / 4)]));
;                         h8[64 * j] = (unsigned long long)pk2(v[j][0], v[j][1]) | ((unsigned long long)pk2(v[j][2], v[j][3]) << 32);
;                         ss += (v[j][0] * v[j][0] + v[j][1] * v[j][1]) + (v[j][2] * v[j][2] + v[j][3] * v[j][3]); }
;                     ss = wave_sum(ss); if (lane < 16) SSQ[(size_t)(MLAT + r) * 16 + lane] = lane == 0 ? ss : 0.f;
;                     unsigned long long* o8 = (unsigned long long*)(AB + (size_t)(MLAT + r) * DM) + lane;
; #pragma unroll
;                     for (int j = 0; j < 4; ++j) { const f32x4 y = v[j] * (*(const f32x4*)(wg + 4 * lane + 256 * j)) * (*(const f32x4*)(wsc + 4 * lane + 256 * j) + 1.0f);
;                         o8[64 * j] = (unsigned long long)pk2(y[0], y[1]) | ((unsigned long long)pk2(y[2], y[3]) << 32); } }
.LBB0_226:
	s_or_b64 exec, exec, s[24:25]
	s_waitcnt lgkmcnt(0)
	global_load_dwordx4 v[28:31], v[0:1], off
	s_mov_b32 s1, 0x5700000
	s_add_i32 s0, s0, s2
	v_lshl_add_u64 v[4:5], v[4:5], 0, s[12:13]
	v_lshl_add_u64 v[6:7], v[6:7], 0, s[14:15]
	v_lshl_add_u64 v[8:9], v[8:9], 0, s[18:19]
	s_cmpk_gt_i32 s0, 0x1ff
	s_waitcnt vmcnt(0)
	v_pk_mul_f32 v[30:31], v[12:13], v[30:31]
	v_pk_mul_f32 v[28:29], v[14:15], v[28:29]
	global_load_dwordx4 v[12:15], v[2:3], off
	s_waitcnt vmcnt(0)
	v_pk_add_f32 v[14:15], v[14:15], 1.0 op_sel_hi:[1,0]
	v_pk_add_f32 v[12:13], v[12:13], 1.0 op_sel_hi:[1,0]
	v_pk_mul_f32 v[14:15], v[30:31], v[14:15]
	v_pk_mul_f32 v[12:13], v[28:29], v[12:13]
	s_nop 0
	v_cvt_pk_bf16_f32 v12, v12, v13
	v_cvt_pk_bf16_f32 v13, v14, v15
	v_add_co_u32_e32 v14, vcc, s1, v10
	s_nop 1
	v_addc_co_u32_e32 v15, vcc, 0, v11, vcc
	global_store_dwordx2 v[14:15], v[12:13], off sc1
	global_load_dwordx4 v[10:13], v[0:1], off offset:1024
	s_waitcnt vmcnt(0)
	v_pk_mul_f32 v[16:17], v[16:17], v[12:13]
	v_pk_mul_f32 v[18:19], v[18:19], v[10:11]
	global_load_dwordx4 v[10:13], v[2:3], off offset:1024
	s_waitcnt vmcnt(0)
	v_pk_add_f32 v[10:11], v[10:11], 1.0 op_sel_hi:[1,0]
	v_pk_add_f32 v[12:13], v[12:13], 1.0 op_sel_hi:[1,0]
	v_pk_mul_f32 v[10:11], v[18:19], v[10:11]
	v_pk_mul_f32 v[12:13], v[16:17], v[12:13]
	v_cvt_pk_bf16_f32 v10, v10, v11
	s_nop 0
	v_cvt_pk_bf16_f32 v11, v12, v13
	global_store_dwordx2 v[14:15], v[10:11], off offset:512 sc1
	global_load_dwordx4 v[10:13], v[0:1], off offset:2048
	s_waitcnt vmcnt(0)
	v_pk_mul_f32 v[16:17], v[20:21], v[12:13]
	v_pk_mul_f32 v[18:19], v[22:23], v[10:11]
	global_load_dwordx4 v[10:13], v[2:3], off offset:2048
	s_waitcnt vmcnt(0)
	v_pk_add_f32 v[10:11], v[10:11], 1.0 op_sel_hi:[1,0]
	v_pk_add_f32 v[12:13], v[12:13], 1.0 op_sel_hi:[1,0]
	v_pk_mul_f32 v[10:11], v[18:19], v[10:11]
	v_pk_mul_f32 v[12:13], v[16:17], v[12:13]
	v_cvt_pk_bf16_f32 v10, v10, v11
	s_nop 0
	v_cvt_pk_bf16_f32 v11, v12, v13
	global_store_dwordx2 v[14:15], v[10:11], off offset:1024 sc1
	global_load_dwordx4 v[10:13], v[0:1], off offset:3072
	s_waitcnt vmcnt(0)
	v_pk_mul_f32 v[16:17], v[24:25], v[12:13]
	v_pk_mul_f32 v[18:19], v[26:27], v[10:11]
	global_load_dwordx4 v[10:13], v[2:3], off offset:3072
	s_waitcnt vmcnt(0)
	v_pk_add_f32 v[10:11], v[10:11], 1.0 op_sel_hi:[1,0]
	v_pk_add_f32 v[12:13], v[12:13], 1.0 op_sel_hi:[1,0]
	v_pk_mul_f32 v[10:11], v[18:19], v[10:11]
	v_pk_mul_f32 v[12:13], v[16:17], v[12:13]
	v_cvt_pk_bf16_f32 v10, v10, v11
	s_nop 0
	v_cvt_pk_bf16_f32 v11, v12, v13
	global_store_dwordx2 v[14:15], v[10:11], off offset:1536 sc1
	s_cbranch_scc1 .LBB0_229
.LBB0_227:
	v_lshl_add_u64 v[10:11], s[6:7], 0, v[6:7]
	v_add_co_u32_e32 v28, vcc, 0x14200000, v10
	v_lshl_add_u64 v[20:21], s[6:7], 0, v[8:9]
	s_nop 0
	v_addc_co_u32_e32 v29, vcc, 0, v11, vcc
	global_load_dwordx2 v[12:13], v[28:29], off
	s_mov_b32 s1, 0xfc00000
	v_add_co_u32_e32 v24, vcc, s1, v20
	s_mov_b32 s1, 0xfe00000
	s_nop 0
	v_addc_co_u32_e32 v25, vcc, 0, v21, vcc
	v_add_co_u32_e32 v26, vcc, s1, v20
	s_brev_b32 s1, 8
	s_nop 0
	v_addc_co_u32_e32 v27, vcc, 0, v21, vcc
	v_add_co_u32_e32 v30, vcc, s1, v20
	s_mov_b32 s1, 0x10200000
	s_nop 0
	v_addc_co_u32_e32 v31, vcc, 0, v21, vcc
	v_add_co_u32_e32 v32, vcc, s1, v20
	global_load_dwordx4 v[16:19], v[26:27], off
	s_nop 0
	v_addc_co_u32_e32 v33, vcc, 0, v21, vcc
	s_waitcnt vmcnt(1)
	v_lshlrev_b32_e32 v22, 16, v12
	v_and_b32_e32 v23, 0xffff0000, v12
	v_lshlrev_b32_e32 v34, 16, v13
	v_and_b32_e32 v35, 0xffff0000, v13
	global_load_dwordx4 v[12:15], v[24:25], off
	s_waitcnt vmcnt(0)
	v_pk_add_f32 v[36:37], v[14:15], v[18:19]
	v_pk_add_f32 v[38:39], v[12:13], v[16:17]
	global_load_dwordx4 v[12:15], v[30:31], off
	global_load_dwordx4 v[16:19], v[32:33], off
	s_waitcnt vmcnt(0)
	v_pk_add_f32 v[14:15], v[14:15], v[18:19]
	v_pk_add_f32 v[12:13], v[12:13], v[16:17]
	v_pk_add_f32 v[14:15], v[36:37], v[14:15]
	v_pk_add_f32 v[16:17], v[38:39], v[12:13]
	v_pk_add_f32 v[12:13], v[14:15], v[34:35]
	v_pk_add_f32 v[14:15], v[16:17], v[22:23]
	s_nop 0
	v_cvt_pk_bf16_f32 v16, v14, v15
	v_cvt_pk_bf16_f32 v17, v12, v13
	global_store_dwordx2 v[28:29], v[16:17], off sc1
	v_mul_f32_e32 v16, v15, v15
	v_mul_f32_e32 v17, v13, v13
	v_fmac_f32_e32 v16, v14, v14
	v_fmac_f32_e32 v17, v12, v12
	v_add_f32_e32 v42, v16, v17
	global_load_dwordx2 v[16:17], v[28:29], off offset:512
	s_waitcnt vmcnt(0)
	v_lshlrev_b32_e32 v34, 16, v16
	v_and_b32_e32 v35, 0xffff0000, v16
	v_lshlrev_b32_e32 v36, 16, v17
	v_and_b32_e32 v37, 0xffff0000, v17
	global_load_dwordx4 v[16:19], v[24:25], off offset:1024
	global_load_dwordx4 v[20:23], v[26:27], off offset:1024
	s_waitcnt vmcnt(0)
	v_pk_add_f32 v[38:39], v[18:19], v[22:23]
	v_pk_add_f32 v[40:41], v[16:17], v[20:21]
	global_load_dwordx4 v[16:19], v[30:31], off offset:1024
	global_load_dwordx4 v[20:23], v[32:33], off offset:1024
	s_waitcnt vmcnt(0)
	v_pk_add_f32 v[18:19], v[18:19], v[22:23]
	v_pk_add_f32 v[16:17], v[16:17], v[20:21]
	v_pk_add_f32 v[18:19], v[38:39], v[18:19]
	v_pk_add_f32 v[20:21], v[40:41], v[16:17]
	v_pk_add_f32 v[16:17], v[18:19], v[36:37]
	v_pk_add_f32 v[18:19], v[20:21], v[34:35]
	s_nop 0
	v_cvt_pk_bf16_f32 v20, v18, v19
	v_cvt_pk_bf16_f32 v21, v16, v17
	global_store_dwordx2 v[28:29], v[20:21], off offset:512 sc1
	v_mul_f32_e32 v20, v19, v19
	v_mul_f32_e32 v21, v17, v17
	v_fmac_f32_e32 v20, v18, v18
	v_fmac_f32_e32 v21, v16, v16
	v_add_f32_e32 v20, v20, v21
	v_add_f32_e32 v46, v42, v20
	global_load_dwordx2 v[20:21], v[28:29], off offset:1024
	s_waitcnt vmcnt(0)
; __device__ __forceinline__ unsigned pk2(float lo, float hi) { return pg8::cvt_pk_bf16(lo, hi); }
; __device__ __forceinline__ float bf_lo(unsigned w) { return __uint_as_float(w << 16); }
; __device__ __forceinline__ float bf_hi(unsigned w) { return __uint_as_float(w & 0xffff0000u); }
; #define SSQ    WSP(float, WS_SSQ)
; __global__ void __launch_bounds__(NWAVES * 64, 2) fwd_kernel(Args args) {
;     ...
;                         v[j] = (f32x4){bf_lo(lo_), bf_hi(lo_), bf_lo(hi_), bf_hi(hi_)} + ((xr[64 * j] + xr[64 * j + MCTX * DM / 4]) + (xr[64 * j + 2 * (MCTX * DM / 4)] + xr[64 * j + 3 * (MCTX * DM / 4)]));
;                         h8[64 * j] = (unsigned long long)pk2(v[j][0], v[j][1]) | ((unsigned long long)pk2(v[j][2], v[j][3]) << 32);
;                         ss += (v[j][0] * v[j][0] + v[j][1] * v[j][1]) + (v[j][2] * v[j][2] + v[j][3] * v[j][3]); }
;                     ss = wave_sum(ss); if (lane < 16) SSQ[(size_t)(MLAT + r) * 16 + lane] = lane == 0 ? ss : 0.f;
;                     unsigned long long* o8 = (unsigned long long*)(AB + (size_t)(MLAT + r) * DM) + lane;
; #pragma unroll
;                     for (int j = 0; j < 4; ++j) { const f32x4 y = v[j] * (*(const f32x4*)(wg + 4 * lane + 256 * j)) * (*(const f32x4*)(wsc + 4 * lane + 256 * j) + 1.0f);
;                         o8[64 * j] = (unsigned long long)pk2(y[0], y[1]) | ((unsigned long long)pk2(y[2], y[3]) << 32); } }
	v_lshlrev_b32_e32 v38, 16, v20
	v_and_b32_e32 v39, 0xffff0000, v20
	v_lshlrev_b32_e32 v40, 16, v21
	v_and_b32_e32 v41, 0xffff0000, v21
	global_load_dwordx4 v[20:23], v[24:25], off offset:2048
	global_load_dwordx4 v[34:37], v[26:27], off offset:2048
	s_waitcnt vmcnt(0)
	v_pk_add_f32 v[42:43], v[22:23], v[36:37]
	v_pk_add_f32 v[44:45], v[20:21], v[34:35]
	global_load_dwordx4 v[20:23], v[30:31], off offset:2048
	global_load_dwordx4 v[34:37], v[32:33], off offset:2048
	s_waitcnt vmcnt(0)
	v_pk_add_f32 v[22:23], v[22:23], v[36:37]
	v_pk_add_f32 v[20:21], v[20:21], v[34:35]
	v_pk_add_f32 v[22:23], v[42:43], v[22:23]
	v_pk_add_f32 v[34:35], v[44:45], v[20:21]
	v_pk_add_f32 v[20:21], v[22:23], v[40:41]
	v_pk_add_f32 v[22:23], v[34:35], v[38:39]
	s_nop 0
	v_cvt_pk_bf16_f32 v34, v22, v23
	v_cvt_pk_bf16_f32 v35, v20, v21
	global_store_dwordx2 v[28:29], v[34:35], off offset:1024 sc1
	v_mul_f32_e32 v34, v23, v23
	v_mul_f32_e32 v35, v21, v21
	v_fmac_f32_e32 v34, v22, v22
	v_fmac_f32_e32 v35, v20, v20
	v_add_f32_e32 v34, v34, v35
	v_add_f32_e32 v42, v46, v34
	global_load_dwordx2 v[34:35], v[28:29], off offset:1536
	s_waitcnt vmcnt(0)
	v_lshlrev_b32_e32 v38, 16, v34
	v_and_b32_e32 v39, 0xffff0000, v34
	v_lshlrev_b32_e32 v40, 16, v35
	v_and_b32_e32 v41, 0xffff0000, v35
	global_load_dwordx4 v[34:37], v[24:25], off offset:3072
	s_nop 0
	global_load_dwordx4 v[24:27], v[26:27], off offset:3072
	s_waitcnt vmcnt(0)
	v_pk_add_f32 v[36:37], v[36:37], v[26:27]
	v_pk_add_f32 v[34:35], v[34:35], v[24:25]
	global_load_dwordx4 v[24:27], v[30:31], off offset:3072
	s_nop 0
	global_load_dwordx4 v[30:33], v[32:33], off offset:3072
	s_waitcnt vmcnt(0)
	v_pk_add_f32 v[26:27], v[26:27], v[32:33]
	v_pk_add_f32 v[24:25], v[24:25], v[30:31]
	v_pk_add_f32 v[26:27], v[36:37], v[26:27]
	v_pk_add_f32 v[30:31], v[34:35], v[24:25]
	v_pk_add_f32 v[24:25], v[26:27], v[40:41]
	v_pk_add_f32 v[26:27], v[30:31], v[38:39]
	s_nop 0
	v_cvt_pk_bf16_f32 v30, v26, v27
	v_cvt_pk_bf16_f32 v31, v24, v25
	global_store_dwordx2 v[28:29], v[30:31], off offset:1536 sc1
	v_mul_f32_e32 v28, v27, v27
	v_mul_f32_e32 v29, v25, v25
	v_fmac_f32_e32 v28, v26, v26
	v_fmac_f32_e32 v29, v24, v24
	v_add_f32_e32 v28, v28, v29
	v_and_b32_e32 v29, 64, v246
	v_add_u32_e32 v29, 64, v29
	v_xor_b32_e32 v30, 1, v246
	v_cmp_lt_i32_e32 vcc, v30, v29
	v_add_f32_e32 v28, v42, v28
	s_nop 0
	v_cndmask_b32_e32 v30, v246, v30, vcc
	v_lshlrev_b32_e32 v30, 2, v30
	ds_bpermute_b32 v30, v30, v28
	s_waitcnt lgkmcnt(0)
	v_add_f32_e32 v28, v28, v30
	v_xor_b32_e32 v30, 2, v246
	v_cmp_lt_i32_e32 vcc, v30, v29
	s_nop 1
	v_cndmask_b32_e32 v30, v246, v30, vcc
	v_lshlrev_b32_e32 v30, 2, v30
	ds_bpermute_b32 v30, v30, v28
	s_waitcnt lgkmcnt(0)
	v_add_f32_e32 v28, v28, v30
	v_xor_b32_e32 v30, 4, v246
	v_cmp_lt_i32_e32 vcc, v30, v29
	s_nop 1
	v_cndmask_b32_e32 v30, v246, v30, vcc
	v_lshlrev_b32_e32 v30, 2, v30
	ds_bpermute_b32 v30, v30, v28
	s_waitcnt lgkmcnt(0)
	v_add_f32_e32 v28, v28, v30
	v_xor_b32_e32 v30, 8, v246
	v_cmp_lt_i32_e32 vcc, v30, v29
	s_nop 1
	v_cndmask_b32_e32 v30, v246, v30, vcc
	v_lshlrev_b32_e32 v30, 2, v30
	ds_bpermute_b32 v30, v30, v28
	s_waitcnt lgkmcnt(0)
	v_add_f32_e32 v28, v28, v30
	v_xor_b32_e32 v30, 16, v246
	v_cmp_lt_i32_e32 vcc, v30, v29
	s_nop 1
	v_cndmask_b32_e32 v30, v246, v30, vcc
	v_lshlrev_b32_e32 v30, 2, v30
	ds_bpermute_b32 v30, v30, v28
	s_waitcnt lgkmcnt(0)
	v_add_f32_e32 v28, v28, v30
	v_xor_b32_e32 v30, 32, v246
	v_cmp_lt_i32_e32 vcc, v30, v29
	s_nop 1
	v_cndmask_b32_e32 v29, v246, v30, vcc
	v_lshlrev_b32_e32 v29, 2, v29
	ds_bpermute_b32 v29, v29, v28
	s_and_saveexec_b64 s[24:25], s[38:39]
	s_cbranch_execz .LBB0_226
	s_waitcnt lgkmcnt(0)
	v_add_f32_e32 v28, v28, v29
	v_lshl_add_u64 v[30:31], s[6:7], 0, v[4:5]
	v_cndmask_b32_e64 v28, 0, v28, s[40:41]
	global_store_dword v[30:31], v28, off sc1
	s_branch .LBB0_226
.LBB0_229:
	s_add_i32 s0, s74, 3
	v_writelane_b32 v254, s0, 2
	s_cmp_lt_i32 s0, s81
	s_cbranch_scc0 .LBB0_158
	s_waitcnt vmcnt(0) lgkmcnt(0)
	s_barrier
	v_cmp_eq_u32_e32 vcc, 0, v215
	s_and_saveexec_b64 s[0:1], vcc
	s_cbranch_execz .Lcs_w
	s_load_dwordx2 s[2:3], s[94:95], 0xb8
	v_mov_b32_e32 v0, 0x2c14
	v_mov_b32_e32 v1, 1
	s_waitcnt lgkmcnt(0)
	s_add_u32 s2, s2, 0xe0000
	s_addc_u32 s3, s3, 0
	global_atomic_add v0, v1, s[2:3]
.Lcs_w:
	s_or_b64 exec, exec, s[0:1]
	s_branch .LBB0_158
	v_readlane_b32 s0, v254, 3
	v_readlane_b32 s1, v254, 4
	s_andn2_b64 vcc, exec, s[0:1]
	s_cbranch_vccnz .LBB0_242
	s_barrier
	s_mov_b64 s[0:1], exec
	v_readlane_b32 s2, v255, 6
	v_readlane_b32 s3, v255, 7
	s_and_b64 s[2:3], s[0:1], s[2:3]
	s_mov_b64 exec, s[2:3]
	s_cbranch_execz .LBB0_241
	v_readlane_b32 s2, v254, 0
	v_readlane_b32 s3, v254, 1
	buffer_wbl2 sc1
	s_waitcnt vmcnt(0)
	s_load_dwordx2 s[2:3], s[2:3], 0x58
	s_mov_b64 s[6:7], exec
	v_mbcnt_lo_u32_b32 v1, s6, 0
	v_mbcnt_hi_u32_b32 v1, s7, v1
	v_cmp_eq_u32_e32 vcc, 0, v1
	s_waitcnt lgkmcnt(0)
	global_load_dword v0, v213, s[2:3] offset:40
	s_and_saveexec_b64 s[12:13], vcc
	s_cbranch_execz .LBB0_234
	s_bcnt1_i32_b64 s4, s[6:7]
	v_mov_b32_e32 v2, s4
	global_atomic_add v2, v213, v2, s[2:3] offset:32 sc0

;     __host__ __device__ bool next(int i, Unit& u) const {
;         const long L = (long)i * G + c; if (L >= nwg) return false;
; template <class Epi, class Sched>
; __device__ __forceinline__ void gemm_phase(PG8_LAS unsigned char* lds, const Gemm g, const Sched& S, const Epi& E, const int tid) {
;     ...
;         const bool has_next = S.next(ui + 1, nxt);
;         const char* nA = has_next ? (const char*)g.A + (size_t)nxt.pm * tstepA + (size_t)nxt.pn * g.a_pn_off + S.koff(nxt) : cA; const char* nB = has_next ? (const char*)g.Bt + (size_t)nxt.pn * tstepB + S.koff(nxt) : cB;
.LBB0_566:
	s_add_i32 s57, s57, 1
	s_mul_i32 s8, s57, s5
	s_mul_hi_u32 s16, s57, s31
	s_add_i32 s16, s16, s8
	s_mul_i32 s8, s57, s31
	s_add_u32 s60, s8, s87
	s_addc_u32 s61, s16, s86
	v_mov_b64_e32 v[0:1], 0x210
	v_cmp_lt_i64_e64 s[40:41], s[60:61], v[0:1]
	v_mov_b64_e32 v[0:1], 0x20f
	v_cmp_gt_i64_e32 vcc, s[60:61], v[0:1]
	s_cbranch_vccnz .LBB0_568
	s_cmp_lt_u32 s60, 0x200
	s_cbranch_scc1 .Lcx_skip
	v_readfirstlane_b32 s100, v215
	s_cmp_lt_u32 s100, 64
	s_cbranch_scc0 .Lcx_w
	v_readlane_b32 s100, v255, 10
	v_readlane_b32 s101, v255, 11
	s_nop 4
	s_load_dwordx2 s[100:101], s[100:101], 0xb8
	v_mov_b32_e32 v0, 0x2c14
	s_waitcnt lgkmcnt(0)
	s_add_u32 s100, s100, 0xe0000
	s_addc_u32 s101, s101, 0
	buffer_inv sc1
	s_mov_b32 s8, 0
.Lcx_p:
	global_load_dword v1, v0, s[100:101] sc1
	s_waitcnt vmcnt(0)
	v_cmp_le_u32_e32 vcc, 0x100, v1
	s_cbranch_vccnz .Lcx_d
	s_sleep 1
	s_add_i32 s8, s8, 1
	s_cmp_lt_u32 s8, 0x100000
	s_cbranch_scc1 .Lcx_p

;     __host__ __device__ bool next(int i, Unit& u) const {
;         const long L = (long)i * G + c; if (L >= nwg) return false;
;         int wgid = (int)L; { const int q = nwg / NXCD, r = nwg % NXCD, xcd = wgid % NXCD, off = wgid / NXCD; wgid = (xcd < r ? xcd * (q + 1) : r * (q + 1) + (xcd - r) * q) + off; }
;         const int nig = WGM * nN, gid = wgid / nig, fm = gid * WGM, gsz = (nM - fm) < WGM ? (nM - fm) : WGM;
;         u.pm = fm + ((wgid % nig) % gsz); u.pn = (wgid % nig) / gsz; return true;
.Lcx_w:
.Lcx_skip:
	s_ashr_i32 s8, s60, 31
	s_lshr_b32 s8, s8, 29
	s_add_i32 s8, s60, s8
	s_ashr_i32 s16, s8, 3
	s_and_b32 s8, s8, -8
	s_sub_i32 s8, s60, s8
	s_cmp_lt_i32 s8, 0
	s_movk_i32 s17, 0x43
	s_cselect_b32 s17, s17, 0x42
	s_lshl_b32 s17, s8, 6
	s_add_i32 s17, s17, s16
	s_sub_i32 s20, s16, 64
	s_lshl_b32 s20, s20, 3
	s_add_i32 s20, s20, s8
	s_addk_i32 s20, 0x200
	s_cmp_lt_i32 s16, 64
	s_cselect_b32 s8, s17, s20
	s_ashr_i32 s16, s8, 31
	s_lshr_b32 s16, s16, 26
	s_add_i32 s16, s8, s16
	s_ashr_i32 s17, s16, 6
	s_lshl_b32 s17, s17, 3
	s_sub_i32 s20, 0x42, s17
	s_min_i32 s20, s20, 8
	s_abs_i32 s21, s20
	v_cvt_f32_u32_e32 v0, s21
	s_sub_i32 s23, 0, s21
	s_andn2_b32 s16, s16, 63
	s_sub_i32 s8, s8, s16
	v_rcp_iflag_f32_e32 v0, v0
	s_abs_i32 s16, s8
	s_xor_b32 s22, s8, s20
	s_ashr_i32 s22, s22, 31
	v_mul_f32_e32 v0, 0x4f7ffffe, v0
	v_cvt_u32_f32_e32 v0, v0
	s_nop 0
	v_readfirstlane_b32 s30, v0
	s_mul_i32 s23, s23, s30
	s_mul_hi_u32 s23, s30, s23
	s_add_i32 s30, s30, s23
	s_mul_hi_u32 s23, s16, s30
	s_mul_i32 s30, s23, s21
	s_sub_i32 s16, s16, s30
	s_add_i32 s33, s23, 1
	s_sub_i32 s30, s16, s21
	s_cmp_ge_u32 s16, s21
	s_cselect_b32 s23, s33, s23
	s_cselect_b32 s16, s30, s16
	s_add_i32 s30, s23, 1
	s_cmp_ge_u32 s16, s21
	s_cselect_b32 s16, s30, s23
	s_xor_b32 s16, s16, s22
	s_sub_i32 s34, s16, s22
	s_mul_i32 s16, s34, s20
	s_sub_i32 s8, s8, s16
	s_add_i32 s64, s17, s8
